# attention inner loop rewritten by hand: branch-free 3-part software pipeline, masked sub-tiles instead of per-wave control flow
# speedup vs baseline: 1.0189x; 1.0189x over previous
; __device__ __forceinline__ void att_qk(const LAS unsigned char* Kb, const bf16x8 (&qf)[2][2], int nst, int j, int qpos, float slope2, int fr, int fq, f32x4 (&sc)[2][4]) {
;     constexpr int KSTR = 272;
; #pragma unroll
;     for (int st = 0; st < 4; ++st) {
;         if (st < nst) {
;             const float d0 = (float)(qpos - (64 * j + 16 * st + 4 * fq));
;             f32x4 s0;
; #pragma unroll
;             for (int e = 0; e < 4; ++e) s0[e] = -slope2 * __builtin_fabsf(d0 - (float)e) - 12.0f;
;             f32x4 s1 = s0;
; #pragma unroll
;             for (int ks = 0; ks < 2; ++ks) {
;                 const bf16x8 k0 = *(const LAS bf16x8*)(Kb + (16 * st + fr) * KSTR + (32 * ks + 8 * fq) * 2);
;                 const bf16x8 k1 = *(const LAS bf16x8*)(Kb + (16 * st + fr) * KSTR + (64 + 32 * ks + 8 * fq) * 2);
;                 s0 = __builtin_amdgcn_mfma_f32_16x16x32_bf16(k0, qf[0][ks], s0, 0, 0, 0);
;                 s1 = __builtin_amdgcn_mfma_f32_16x16x32_bf16(k1, qf[1][ks], s1, 0, 0, 0);
;             }
;             sc[0][st] = s0; sc[1][st] = s1;
;         }
;     }
; }
; __device__ __forceinline__ void att_pv(const LAS unsigned char* Vb, int nst, const f32x4 (&sc)[2][4], f32x4 (&O)[2][8], float& l0, float& l1, int fr, int fq) {
;     constexpr int VSTR = 144;
;     if (nst <= 0) return;
;     unsigned pw[2][4][2];
; #pragma unroll
;     for (int st = 0; st < 4; ++st) {
;         if (st < nst) {
;             float p0[4], p1[4];
; #pragma unroll
;             for (int e = 0; e < 4; ++e) { p0[e] = __builtin_amdgcn_exp2f(sc[0][st][e]); p1[e] = __builtin_amdgcn_exp2f(sc[1][st][e]); l0 += p0[e]; l1 += p1[e]; }
;             pw[0][st][0] = pk2(p0[0], p0[1]); pw[0][st][1] = pk2(p0[2], p0[3]); pw[1][st][0] = pk2(p1[0], p1[1]); pw[1][st][1] = pk2(p1[2], p1[3]);
;         } else { pw[0][st][0] = 0u; pw[0][st][1] = 0u; pw[1][st][0] = 0u; pw[1][st][1] = 0u; }
;     }
; #pragma unroll
;     for (int ks2 = 0; ks2 < 2; ++ks2) {
;         if (ks2 == 0 || nst == 4) {
;             const u32x4 a0 = (u32x4){pw[0][2 * ks2][0], pw[0][2 * ks2][1], pw[0][2 * ks2 + 1][0], pw[0][2 * ks2 + 1][1]};
;             const u32x4 a1 = (u32x4){pw[1][2 * ks2][0], pw[1][2 * ks2][1], pw[1][2 * ks2 + 1][0], pw[1][2 * ks2 + 1][1]};
;             const bf16x8 pf0 = __builtin_bit_cast(bf16x8, a0), pf1 = __builtin_bit_cast(bf16x8, a1);
; #pragma unroll
.LBB0_619:
	s_add_i32 s0, s6, 16
	s_lshl_b32 s0, s0, 10
	s_lshl_b32 s1, s34, 1
	s_add_u32 s22, s10, s0
	s_addc_u32 s23, s11, 0
	s_add_u32 s22, s22, s1
	s_addc_u32 s23, s23, 0
	s_bfe_u32 s0, s17, 0x50003
	s_mul_i32 s0, s0, 0x84000
	s_add_u32 s24, s86, 0xb700000
	s_addc_u32 s25, s87, 0
	s_add_u32 s24, s24, s0
	s_addc_u32 s25, s25, 0
	s_mov_b32 s18, 0xc6ea6000
	s_xor_b32 s19, s20, 0x80000000
	s_movk_i32 s46, 0x1080
	s_mov_b32 s4, 0
	v_and_b32_e32 v46, 3, v209
	v_lshlrev_b32_e32 v46, 4, v46
	v_mad_u32_u24 v46, v240, s46, v46
	v_add_u32_e32 v47, s31, v249
	v_add_u32_e32 v47, 16, v47
	v_cvt_f32_i32_e32 v47, v47
	v_add_f32_e32 v47, 0xc2800000, v47
	v_mov_b32_e32 v236, 0
	v_mov_b32_e32 v237, 0
	s_mov_b32 s5, 1
	s_cmp_le_u32 s5, s37
	s_cselect_b32 s45, s16, s18
	s_add_i32 s0, s37, 1
	s_cmp_le_u32 s5, s0
	s_cselect_b32 s43, s16, s18
	v_mov_b32_e32 v4, s43
	v_fma_f32 v48, |v47|, s19, v4
	v_subrev_f32_e32 v49, 0x3f800000, v47
	v_fma_f32 v49, |v49|, s19, v4
	v_subrev_f32_e32 v50, 0x40000000, v47
	v_fma_f32 v50, |v50|, s19, v4
	v_subrev_f32_e32 v51, 0x40400000, v47
	v_fma_f32 v51, |v51|, s19, v4
	v_mov_b32_e32 v4, s45
	v_subrev_f32_e32 v52, 0x41800000, v47
	v_fma_f32 v52, |v52|, s19, v4
	v_subrev_f32_e32 v53, 0x41880000, v47
	v_fma_f32 v53, |v53|, s19, v4
	v_subrev_f32_e32 v54, 0x41900000, v47
	v_fma_f32 v54, |v54|, s19, v4
	v_subrev_f32_e32 v55, 0x41980000, v47
	v_fma_f32 v55, |v55|, s19, v4
	v_subrev_f32_e32 v56, 0x42000000, v47
	v_fma_f32 v56, |v56|, s19, v4
	v_subrev_f32_e32 v57, 0x42040000, v47
	v_fma_f32 v57, |v57|, s19, v4
	v_subrev_f32_e32 v58, 0x42080000, v47
	v_fma_f32 v58, |v58|, s19, v4
	v_subrev_f32_e32 v59, 0x420c0000, v47
	v_fma_f32 v59, |v59|, s19, v4
	v_subrev_f32_e32 v60, 0x42400000, v47
	v_fma_f32 v60, |v60|, s19, v4
	v_subrev_f32_e32 v61, 0x42440000, v47
	v_fma_f32 v61, |v61|, s19, v4
	v_subrev_f32_e32 v62, 0x42480000, v47
	v_fma_f32 v62, |v62|, s19, v4
	v_subrev_f32_e32 v63, 0x424c0000, v47
	v_fma_f32 v63, |v63|, s19, v4
	v_add_f32_e32 v47, 0xc2800000, v47
.Latt_it_e:
	s_sub_i32 s1, s36, 1
	s_add_i32 s0, s4, 2
	s_min_u32 s0, s0, s1
	s_add_i32 s5, s4, 1
	s_min_u32 s5, s5, s1
	s_lshl_b32 s0, s0, 6
	s_lshl_b32 s5, s5, 7
	v_add_u32_e32 v223, s0, v243
	v_min_u32_e32 v223, 0x7ff, v223
	v_lshl_add_u32 v223, v223, 10, v224
	s_add_u32 s26, s24, s5
	s_addc_u32 s27, s25, 0
	global_load_dwordx4 v[84:87], v223, s[22:23]
	global_load_dwordx4 v[88:91], v223, s[22:23] offset:128
	global_load_dwordx4 v[92:95], v46, s[26:27]
	global_load_dwordx4 v[96:99], v46, s[26:27] offset:64
	ds_read_b128 v[6:9], v253 offset:17536
	ds_read_b128 v[10:13], v253 offset:17408
	ds_read_b128 v[14:17], v253 offset:21888
	ds_read_b128 v[18:21], v253 offset:21760
	ds_read_b128 v[22:25], v253 offset:26240
	ds_read_b128 v[26:29], v253 offset:26112
	ds_read_b128 v[30:33], v253 offset:30592
	ds_read_b128 v[34:37], v253 offset:30464
	s_waitcnt lgkmcnt(7)
	v_mfma_f32_16x16x32_bf16 v[64:67], v[6:9], v[112:115], v[48:51]
	ds_read_b128 v[6:9], v253 offset:17600
	v_exp_f32_e32 v152, v152
	v_exp_f32_e32 v153, v153
	s_waitcnt lgkmcnt(7)
	v_mfma_f32_16x16x32_bf16 v[48:51], v[10:13], v[80:83], v[48:51]
	ds_read_b128 v[10:13], v253 offset:17472
	v_exp_f32_e32 v154, v154
	v_exp_f32_e32 v155, v155
	s_waitcnt lgkmcnt(7)
	v_mfma_f32_16x16x32_bf16 v[68:71], v[14:17], v[112:115], v[52:55]
	ds_read_b128 v[14:17], v253 offset:21952
	v_exp_f32_e32 v156, v156
	v_exp_f32_e32 v157, v157
	s_waitcnt lgkmcnt(7)
	v_mfma_f32_16x16x32_bf16 v[52:55], v[18:21], v[80:83], v[52:55]
	ds_read_b128 v[18:21], v253 offset:21824
	v_exp_f32_e32 v158, v158
	v_exp_f32_e32 v159, v159
	s_waitcnt lgkmcnt(7)
	v_mfma_f32_16x16x32_bf16 v[72:75], v[22:25], v[112:115], v[56:59]
	ds_read_b128 v[22:25], v253 offset:26304
	v_exp_f32_e32 v168, v168
	v_exp_f32_e32 v169, v169
	s_waitcnt lgkmcnt(7)
	v_mfma_f32_16x16x32_bf16 v[56:59], v[26:29], v[80:83], v[56:59]
	ds_read_b128 v[26:29], v253 offset:26176
	v_exp_f32_e32 v170, v170
	v_exp_f32_e32 v171, v171
	s_waitcnt lgkmcnt(7)
	v_mfma_f32_16x16x32_bf16 v[76:79], v[30:33], v[112:115], v[60:63]
	ds_read_b128 v[30:33], v253 offset:30656
	v_exp_f32_e32 v172, v172
	v_exp_f32_e32 v173, v173
	s_waitcnt lgkmcnt(7)
	v_mfma_f32_16x16x32_bf16 v[60:63], v[34:37], v[80:83], v[60:63]
	ds_read_b128 v[34:37], v253 offset:30528
	v_exp_f32_e32 v174, v174
	v_exp_f32_e32 v175, v175
	s_waitcnt lgkmcnt(7)
	v_mfma_f32_16x16x32_bf16 v[64:67], v[6:9], v[128:131], v[64:67]
	ds_read_b64 v[6:7], v245 offset:34816
	ds_read_b64 v[8:9], v245 offset:34848
	v_cvt_pk_bf16_f32 v38, v152, v153
	v_cvt_pk_bf16_f32 v39, v154, v155
	s_waitcnt lgkmcnt(8)
	v_mfma_f32_16x16x32_bf16 v[48:51], v[10:13], v[104:107], v[48:51]
	ds_read_b64 v[10:11], v245 offset:37120
	ds_read_b64 v[12:13], v245 offset:37152
	v_cvt_pk_bf16_f32 v42, v156, v157
	v_cvt_pk_bf16_f32 v43, v158, v159
	s_waitcnt lgkmcnt(9)
	v_mfma_f32_16x16x32_bf16 v[68:71], v[14:17], v[128:131], v[68:71]
	ds_read_b64 v[14:15], v245 offset:39424
	ds_read_b64 v[16:17], v245 offset:39456
	v_pk_add_f32 v[234:235], v[234:235], v[152:153]
	v_pk_add_f32 v[234:235], v[234:235], v[154:155]
	s_waitcnt lgkmcnt(10)
	v_mfma_f32_16x16x32_bf16 v[52:55], v[18:21], v[104:107], v[52:55]
	ds_read_b64 v[18:19], v245 offset:41728
	ds_read_b64 v[20:21], v245 offset:41760
	v_pk_add_f32 v[236:237], v[236:237], v[156:157]
	v_pk_add_f32 v[236:237], v[236:237], v[158:159]
	s_waitcnt lgkmcnt(11)
	v_mfma_f32_16x16x32_bf16 v[72:75], v[22:25], v[128:131], v[72:75]
	ds_read_b64 v[22:23], v245 offset:44032
	ds_read_b64 v[24:25], v245 offset:44064
	v_cvt_pk_bf16_f32 v40, v168, v169
	v_cvt_pk_bf16_f32 v41, v170, v171
	s_waitcnt lgkmcnt(12)
; __device__ __forceinline__ void att_pv(const LAS unsigned char* Vb, int nst, const f32x4 (&sc)[2][4], f32x4 (&O)[2][8], float& l0, float& l1, int fr, int fq) {
;     constexpr int VSTR = 144;
;     if (nst <= 0) return;
;     unsigned pw[2][4][2];
; #pragma unroll
;     for (int st = 0; st < 4; ++st) {
;         if (st < nst) {
;             float p0[4], p1[4];
; #pragma unroll
;             for (int e = 0; e < 4; ++e) { p0[e] = __builtin_amdgcn_exp2f(sc[0][st][e]); p1[e] = __builtin_amdgcn_exp2f(sc[1][st][e]); l0 += p0[e]; l1 += p1[e]; }
;             pw[0][st][0] = pk2(p0[0], p0[1]); pw[0][st][1] = pk2(p0[2], p0[3]); pw[1][st][0] = pk2(p1[0], p1[1]); pw[1][st][1] = pk2(p1[2], p1[3]);
;         } else { pw[0][st][0] = 0u; pw[0][st][1] = 0u; pw[1][st][0] = 0u; pw[1][st][1] = 0u; }
;     }
; #pragma unroll
;     for (int ks2 = 0; ks2 < 2; ++ks2) {
;         if (ks2 == 0 || nst == 4) {
;             const u32x4 a0 = (u32x4){pw[0][2 * ks2][0], pw[0][2 * ks2][1], pw[0][2 * ks2 + 1][0], pw[0][2 * ks2 + 1][1]};
;             const u32x4 a1 = (u32x4){pw[1][2 * ks2][0], pw[1][2 * ks2][1], pw[1][2 * ks2 + 1][0], pw[1][2 * ks2 + 1][1]};
;             const bf16x8 pf0 = __builtin_bit_cast(bf16x8, a0), pf1 = __builtin_bit_cast(bf16x8, a1);
; #pragma unroll
;             for (int dt = 0; dt < 8; ++dt) {
;                 const LAS unsigned char* vp = Vb + (16 * dt + fr) * VSTR + (32 * ks2 + 4 * fq) * 2;
;                 const u32x2 va = *(const LAS u32x2*)vp, vb2 = *(const LAS u32x2*)(vp + 32);
;                 const bf16x8 vf = __builtin_bit_cast(bf16x8, (u32x4){va.x, va.y, vb2.x, vb2.y});
;                 O[0][dt] = __builtin_amdgcn_mfma_f32_16x16x32_bf16(vf, pf0, O[0][dt], 0, 0, 0);
;                 O[1][dt] = __builtin_amdgcn_mfma_f32_16x16x32_bf16(vf, pf1, O[1][dt], 0, 0, 0);
;             }
;         }
;     }
; }
; __device__ __forceinline__ void attn_phase(const Params& P, LAS unsigned char* lds, int tid, int wid, int lane) {
;     ...
;             if (j + 1 < nt) { if (j + 2 < nt) ATT_LOADK(a, j + 2); ATT_LOADV(a, j + 1); }
;             if (j + 1 < nt) att_qk(lds + KBUF, qf, ATT_NST(j + 1), j + 1, qpos, slope2, fr, fq, scB);
;             att_pv(lds + VOFF, ATT_NST(j), scA, O, l0, l1, fr, fq);
;             if (j + 1 < nt) { if (j + 2 < nt) ATT_WRITEK(a, 0); ATT_WRITEV(a, 1); }
;             ATT_BAR();
;             if (j + 1 >= nt) break;
	v_mfma_f32_16x16x32_bf16 v[56:59], v[26:29], v[104:107], v[56:59]
	ds_read_b64 v[26:27], v245 offset:46336
	ds_read_b64 v[28:29], v245 offset:46368
	v_cvt_pk_bf16_f32 v44, v172, v173
	v_cvt_pk_bf16_f32 v45, v174, v175
	s_waitcnt lgkmcnt(13)
	v_mfma_f32_16x16x32_bf16 v[76:79], v[30:33], v[128:131], v[76:79]
	ds_read_b64 v[30:31], v245 offset:48640
	ds_read_b64 v[32:33], v245 offset:48672
	v_pk_add_f32 v[234:235], v[234:235], v[168:169]
	v_pk_add_f32 v[234:235], v[234:235], v[170:171]
	s_waitcnt lgkmcnt(14)
	v_mfma_f32_16x16x32_bf16 v[60:63], v[34:37], v[104:107], v[60:63]
	ds_read_b64 v[34:35], v245 offset:50944
	ds_read_b64 v[36:37], v245 offset:50976
	v_pk_add_f32 v[236:237], v[236:237], v[172:173]
	v_pk_add_f32 v[236:237], v[236:237], v[174:175]
	s_waitcnt lgkmcnt(14)
	v_mfma_f32_16x16x32_bf16 v[184:187], v[6:9], v[38:41], v[184:187]
	v_exp_f32_e32 v192, v192
	v_exp_f32_e32 v193, v193
	v_mfma_f32_16x16x32_bf16 v[188:191], v[6:9], v[42:45], v[188:191]
	ds_read_b64 v[6:7], v245 offset:34880
	ds_read_b64 v[8:9], v245 offset:34912
	v_exp_f32_e32 v194, v194
	v_exp_f32_e32 v195, v195
	s_waitcnt lgkmcnt(14)
	v_mfma_f32_16x16x32_bf16 v[180:183], v[10:13], v[38:41], v[180:183]
	v_exp_f32_e32 v196, v196
	v_exp_f32_e32 v197, v197
	v_mfma_f32_16x16x32_bf16 v[176:179], v[10:13], v[42:45], v[176:179]
	ds_read_b64 v[10:11], v245 offset:37184
	ds_read_b64 v[12:13], v245 offset:37216
	v_exp_f32_e32 v198, v198
	v_exp_f32_e32 v199, v199
	s_waitcnt lgkmcnt(14)
	v_mfma_f32_16x16x32_bf16 v[164:167], v[14:17], v[38:41], v[164:167]
	v_exp_f32_e32 v200, v200
	v_exp_f32_e32 v201, v201
	v_mfma_f32_16x16x32_bf16 v[160:163], v[14:17], v[42:45], v[160:163]
	ds_read_b64 v[14:15], v245 offset:39488
	ds_read_b64 v[16:17], v245 offset:39520
	v_exp_f32_e32 v202, v202
	v_exp_f32_e32 v203, v203
	s_waitcnt lgkmcnt(14)
	v_mfma_f32_16x16x32_bf16 v[148:151], v[18:21], v[38:41], v[148:151]
	v_exp_f32_e32 v204, v204
	v_exp_f32_e32 v205, v205
	v_mfma_f32_16x16x32_bf16 v[144:147], v[18:21], v[42:45], v[144:147]
	ds_read_b64 v[18:19], v245 offset:41792
	ds_read_b64 v[20:21], v245 offset:41824
	v_exp_f32_e32 v206, v206
	v_exp_f32_e32 v207, v207
	s_waitcnt lgkmcnt(14)
	v_mfma_f32_16x16x32_bf16 v[140:143], v[22:25], v[38:41], v[140:143]
	v_cvt_pk_bf16_f32 v0, v192, v193
	v_cvt_pk_bf16_f32 v1, v194, v195
	v_mfma_f32_16x16x32_bf16 v[136:139], v[22:25], v[42:45], v[136:139]
	ds_read_b64 v[22:23], v245 offset:44096
	ds_read_b64 v[24:25], v245 offset:44128
	v_cvt_pk_bf16_f32 v230, v196, v197
	v_cvt_pk_bf16_f32 v231, v198, v199
	s_waitcnt lgkmcnt(14)
	v_mfma_f32_16x16x32_bf16 v[132:135], v[26:29], v[38:41], v[132:135]
	v_pk_add_f32 v[234:235], v[234:235], v[192:193]
	v_pk_add_f32 v[234:235], v[234:235], v[194:195]
	v_mfma_f32_16x16x32_bf16 v[124:127], v[26:29], v[42:45], v[124:127]
	ds_read_b64 v[26:27], v245 offset:46400
	ds_read_b64 v[28:29], v245 offset:46432
	v_pk_add_f32 v[236:237], v[236:237], v[196:197]
	v_pk_add_f32 v[236:237], v[236:237], v[198:199]
	s_waitcnt lgkmcnt(14)
	v_mfma_f32_16x16x32_bf16 v[120:123], v[30:33], v[38:41], v[120:123]
	v_cvt_pk_bf16_f32 v2, v200, v201
	v_cvt_pk_bf16_f32 v3, v202, v203
	v_mfma_f32_16x16x32_bf16 v[116:119], v[30:33], v[42:45], v[116:119]
	ds_read_b64 v[30:31], v245 offset:48704
	ds_read_b64 v[32:33], v245 offset:48736
	v_cvt_pk_bf16_f32 v232, v204, v205
	v_cvt_pk_bf16_f32 v233, v206, v207
	s_waitcnt lgkmcnt(14)
	v_mfma_f32_16x16x32_bf16 v[108:111], v[34:37], v[38:41], v[108:111]
	v_pk_add_f32 v[234:235], v[234:235], v[200:201]
	v_pk_add_f32 v[234:235], v[234:235], v[202:203]
	v_mfma_f32_16x16x32_bf16 v[100:103], v[34:37], v[42:45], v[100:103]
	ds_read_b64 v[34:35], v245 offset:51008
	ds_read_b64 v[36:37], v245 offset:51040
	v_pk_add_f32 v[236:237], v[236:237], v[204:205]
	v_pk_add_f32 v[236:237], v[236:237], v[206:207]
	s_add_i32 s5, s4, 2
	s_cmp_le_u32 s5, s37
	s_cselect_b32 s45, s16, s18
	s_add_i32 s0, s37, 1
	s_cmp_le_u32 s5, s0
	s_cselect_b32 s43, s16, s18
	s_waitcnt vmcnt(0)
	ds_write_b128 v251, v[84:87] offset:0
	ds_write_b128 v251, v[88:91] offset:128
	ds_write_b128 v252, v[92:95] offset:53248
	ds_write_b128 v252, v[96:99] offset:53312
	s_waitcnt lgkmcnt(15)
	v_mfma_f32_16x16x32_bf16 v[184:187], v[6:9], v[0:3], v[184:187]
	v_mov_b32_e32 v4, s43
	v_fma_f32 v152, |v47|, s19, v4
	v_subrev_f32_e32 v153, 0x3f800000, v47
	v_mfma_f32_16x16x32_bf16 v[188:191], v[6:9], v[230:233], v[188:191]
	v_fma_f32 v153, |v153|, s19, v4
	v_subrev_f32_e32 v154, 0x40000000, v47
	v_fma_f32 v154, |v154|, s19, v4
	s_waitcnt lgkmcnt(15)
	v_mfma_f32_16x16x32_bf16 v[180:183], v[10:13], v[0:3], v[180:183]
	v_subrev_f32_e32 v155, 0x40400000, v47
	v_fma_f32 v155, |v155|, s19, v4
	v_mfma_f32_16x16x32_bf16 v[176:179], v[10:13], v[230:233], v[176:179]
	v_mov_b32_e32 v4, s45
	v_subrev_f32_e32 v168, 0x41800000, v47
	s_waitcnt lgkmcnt(14)
	v_mfma_f32_16x16x32_bf16 v[164:167], v[14:17], v[0:3], v[164:167]
	v_fma_f32 v168, |v168|, s19, v4
	v_subrev_f32_e32 v169, 0x41880000, v47
	v_mfma_f32_16x16x32_bf16 v[160:163], v[14:17], v[230:233], v[160:163]
	v_fma_f32 v169, |v169|, s19, v4
	v_subrev_f32_e32 v170, 0x41900000, v47
	s_waitcnt lgkmcnt(12)
	v_mfma_f32_16x16x32_bf16 v[148:151], v[18:21], v[0:3], v[148:151]
	v_fma_f32 v170, |v170|, s19, v4
	v_subrev_f32_e32 v171, 0x41980000, v47
	v_mfma_f32_16x16x32_bf16 v[144:147], v[18:21], v[230:233], v[144:147]
	v_fma_f32 v171, |v171|, s19, v4
	v_subrev_f32_e32 v192, 0x42000000, v47
	s_waitcnt lgkmcnt(10)
	v_mfma_f32_16x16x32_bf16 v[140:143], v[22:25], v[0:3], v[140:143]
	v_fma_f32 v192, |v192|, s19, v4
	v_subrev_f32_e32 v193, 0x42040000, v47
	v_mfma_f32_16x16x32_bf16 v[136:139], v[22:25], v[230:233], v[136:139]
	v_fma_f32 v193, |v193|, s19, v4
	v_subrev_f32_e32 v194, 0x42080000, v47
	s_waitcnt lgkmcnt(8)
	v_mfma_f32_16x16x32_bf16 v[132:135], v[26:29], v[0:3], v[132:135]
	v_fma_f32 v194, |v194|, s19, v4
	v_subrev_f32_e32 v195, 0x420c0000, v47
	v_mfma_f32_16x16x32_bf16 v[124:127], v[26:29], v[230:233], v[124:127]
	v_fma_f32 v195, |v195|, s19, v4
	v_subrev_f32_e32 v200, 0x42400000, v47
	s_waitcnt lgkmcnt(6)
	v_mfma_f32_16x16x32_bf16 v[120:123], v[30:33], v[0:3], v[120:123]
	v_fma_f32 v200, |v200|, s19, v4
	v_subrev_f32_e32 v201, 0x42440000, v47
	v_mfma_f32_16x16x32_bf16 v[116:119], v[30:33], v[230:233], v[116:119]
	v_fma_f32 v201, |v201|, s19, v4
	v_subrev_f32_e32 v202, 0x42480000, v47
	s_waitcnt lgkmcnt(4)
	v_mfma_f32_16x16x32_bf16 v[108:111], v[34:37], v[0:3], v[108:111]
	v_fma_f32 v202, |v202|, s19, v4
	v_subrev_f32_e32 v203, 0x424c0000, v47
	v_mfma_f32_16x16x32_bf16 v[100:103], v[34:37], v[230:233], v[100:103]
	v_fma_f32 v203, |v203|, s19, v4
	v_add_f32_e32 v47, 0xc2800000, v47
	s_waitcnt lgkmcnt(0)
	s_barrier
	s_add_i32 s4, s4, 1
	s_cmp_ge_u32 s4, s36
	s_cbranch_scc1 .Latt_exit
; __device__ __forceinline__ void att_qk(const LAS unsigned char* Kb, const bf16x8 (&qf)[2][2], int nst, int j, int qpos, float slope2, int fr, int fq, f32x4 (&sc)[2][4]) {
;     constexpr int KSTR = 272;
; #pragma unroll
;     for (int st = 0; st < 4; ++st) {
;         if (st < nst) {
;             const float d0 = (float)(qpos - (64 * j + 16 * st + 4 * fq));
;             f32x4 s0;
; #pragma unroll
;             for (int e = 0; e < 4; ++e) s0[e] = -slope2 * __builtin_fabsf(d0 - (float)e) - 12.0f;
;             f32x4 s1 = s0;
; #pragma unroll
;             for (int ks = 0; ks < 2; ++ks) {
;                 const bf16x8 k0 = *(const LAS bf16x8*)(Kb + (16 * st + fr) * KSTR + (32 * ks + 8 * fq) * 2);
;                 const bf16x8 k1 = *(const LAS bf16x8*)(Kb + (16 * st + fr) * KSTR + (64 + 32 * ks + 8 * fq) * 2);
;                 s0 = __builtin_amdgcn_mfma_f32_16x16x32_bf16(k0, qf[0][ks], s0, 0, 0, 0);
;                 s1 = __builtin_amdgcn_mfma_f32_16x16x32_bf16(k1, qf[1][ks], s1, 0, 0, 0);
;             }
;             sc[0][st] = s0; sc[1][st] = s1;
;         }
;     }
; }
; __device__ __forceinline__ void att_pv(const LAS unsigned char* Vb, int nst, const f32x4 (&sc)[2][4], f32x4 (&O)[2][8], float& l0, float& l1, int fr, int fq) {
;     constexpr int VSTR = 144;
;     if (nst <= 0) return;
;     unsigned pw[2][4][2];
; #pragma unroll
;     for (int st = 0; st < 4; ++st) {
;         if (st < nst) {
;             float p0[4], p1[4];
; #pragma unroll
;             for (int e = 0; e < 4; ++e) { p0[e] = __builtin_amdgcn_exp2f(sc[0][st][e]); p1[e] = __builtin_amdgcn_exp2f(sc[1][st][e]); l0 += p0[e]; l1 += p1[e]; }
;             pw[0][st][0] = pk2(p0[0], p0[1]); pw[0][st][1] = pk2(p0[2], p0[3]); pw[1][st][0] = pk2(p1[0], p1[1]); pw[1][st][1] = pk2(p1[2], p1[3]);
;         } else { pw[0][st][0] = 0u; pw[0][st][1] = 0u; pw[1][st][0] = 0u; pw[1][st][1] = 0u; }
;     }
; #pragma unroll
;     for (int ks2 = 0; ks2 < 2; ++ks2) {
;         if (ks2 == 0 || nst == 4) {
;             const u32x4 a0 = (u32x4){pw[0][2 * ks2][0], pw[0][2 * ks2][1], pw[0][2 * ks2 + 1][0], pw[0][2 * ks2 + 1][1]};
;             const u32x4 a1 = (u32x4){pw[1][2 * ks2][0], pw[1][2 * ks2][1], pw[1][2 * ks2 + 1][0], pw[1][2 * ks2 + 1][1]};
;             const bf16x8 pf0 = __builtin_bit_cast(bf16x8, a0), pf1 = __builtin_bit_cast(bf16x8, a1);
; #pragma unroll
.Latt_it_o:
	s_sub_i32 s1, s36, 1
	s_add_i32 s0, s4, 2
	s_min_u32 s0, s0, s1
	s_add_i32 s5, s4, 1
	s_min_u32 s5, s5, s1
	s_lshl_b32 s0, s0, 6
	s_lshl_b32 s5, s5, 7
	v_add_u32_e32 v223, s0, v243
	v_min_u32_e32 v223, 0x7ff, v223
	v_lshl_add_u32 v223, v223, 10, v224
	s_add_u32 s26, s24, s5
	s_addc_u32 s27, s25, 0
	global_load_dwordx4 v[84:87], v223, s[22:23]
	global_load_dwordx4 v[88:91], v223, s[22:23] offset:128
	global_load_dwordx4 v[92:95], v46, s[26:27]
	global_load_dwordx4 v[96:99], v46, s[26:27] offset:64
	ds_read_b128 v[6:9], v253 offset:128
	ds_read_b128 v[10:13], v253 offset:0
	ds_read_b128 v[14:17], v253 offset:4480
	ds_read_b128 v[18:21], v253 offset:4352
	ds_read_b128 v[22:25], v253 offset:8832
	ds_read_b128 v[26:29], v253 offset:8704
	ds_read_b128 v[30:33], v253 offset:13184
	ds_read_b128 v[34:37], v253 offset:13056
	s_waitcnt lgkmcnt(7)
	v_mfma_f32_16x16x32_bf16 v[156:159], v[6:9], v[112:115], v[152:155]
	ds_read_b128 v[6:9], v253 offset:192
	v_exp_f32_e32 v48, v48
	v_exp_f32_e32 v49, v49
	s_waitcnt lgkmcnt(7)
	v_mfma_f32_16x16x32_bf16 v[152:155], v[10:13], v[80:83], v[152:155]
	ds_read_b128 v[10:13], v253 offset:64
	v_exp_f32_e32 v50, v50
	v_exp_f32_e32 v51, v51
	s_waitcnt lgkmcnt(7)
	v_mfma_f32_16x16x32_bf16 v[172:175], v[14:17], v[112:115], v[168:171]
	ds_read_b128 v[14:17], v253 offset:4544
	v_exp_f32_e32 v64, v64
	v_exp_f32_e32 v65, v65
	s_waitcnt lgkmcnt(7)
	v_mfma_f32_16x16x32_bf16 v[168:171], v[18:21], v[80:83], v[168:171]
	ds_read_b128 v[18:21], v253 offset:4416
	v_exp_f32_e32 v66, v66
	v_exp_f32_e32 v67, v67
	s_waitcnt lgkmcnt(7)
	v_mfma_f32_16x16x32_bf16 v[196:199], v[22:25], v[112:115], v[192:195]
	ds_read_b128 v[22:25], v253 offset:8896
	v_exp_f32_e32 v52, v52
	v_exp_f32_e32 v53, v53
	s_waitcnt lgkmcnt(7)
	v_mfma_f32_16x16x32_bf16 v[192:195], v[26:29], v[80:83], v[192:195]
	ds_read_b128 v[26:29], v253 offset:8768
	v_exp_f32_e32 v54, v54
	v_exp_f32_e32 v55, v55
	s_waitcnt lgkmcnt(7)
	v_mfma_f32_16x16x32_bf16 v[204:207], v[30:33], v[112:115], v[200:203]
	ds_read_b128 v[30:33], v253 offset:13248
	v_exp_f32_e32 v68, v68
	v_exp_f32_e32 v69, v69
	s_waitcnt lgkmcnt(7)
	v_mfma_f32_16x16x32_bf16 v[200:203], v[34:37], v[80:83], v[200:203]
	ds_read_b128 v[34:37], v253 offset:13120
	v_exp_f32_e32 v70, v70
	v_exp_f32_e32 v71, v71
	s_waitcnt lgkmcnt(7)
	v_mfma_f32_16x16x32_bf16 v[156:159], v[6:9], v[128:131], v[156:159]
	ds_read_b64 v[6:7], v246 offset:0
	ds_read_b64 v[8:9], v246 offset:32
	v_cvt_pk_bf16_f32 v38, v48, v49
	v_cvt_pk_bf16_f32 v39, v50, v51
	s_waitcnt lgkmcnt(8)
	v_mfma_f32_16x16x32_bf16 v[152:155], v[10:13], v[104:107], v[152:155]
	ds_read_b64 v[10:11], v246 offset:2304
	ds_read_b64 v[12:13], v246 offset:2336
	v_cvt_pk_bf16_f32 v42, v64, v65
	v_cvt_pk_bf16_f32 v43, v66, v67
	s_waitcnt lgkmcnt(9)
	v_mfma_f32_16x16x32_bf16 v[172:175], v[14:17], v[128:131], v[172:175]
	ds_read_b64 v[14:15], v246 offset:4608
	ds_read_b64 v[16:17], v246 offset:4640
	v_pk_add_f32 v[234:235], v[234:235], v[48:49]
	v_pk_add_f32 v[234:235], v[234:235], v[50:51]
	s_waitcnt lgkmcnt(10)
	v_mfma_f32_16x16x32_bf16 v[168:171], v[18:21], v[104:107], v[168:171]
	ds_read_b64 v[18:19], v246 offset:6912
	ds_read_b64 v[20:21], v246 offset:6944
	v_pk_add_f32 v[236:237], v[236:237], v[64:65]
	v_pk_add_f32 v[236:237], v[236:237], v[66:67]
	s_waitcnt lgkmcnt(11)
	v_mfma_f32_16x16x32_bf16 v[196:199], v[22:25], v[128:131], v[196:199]
	ds_read_b64 v[22:23], v246 offset:9216
	ds_read_b64 v[24:25], v246 offset:9248
	v_cvt_pk_bf16_f32 v40, v52, v53
	v_cvt_pk_bf16_f32 v41, v54, v55
	s_waitcnt lgkmcnt(12)
	v_mfma_f32_16x16x32_bf16 v[192:195], v[26:29], v[104:107], v[192:195]
	ds_read_b64 v[26:27], v246 offset:11520
	ds_read_b64 v[28:29], v246 offset:11552
	v_cvt_pk_bf16_f32 v44, v68, v69
	v_cvt_pk_bf16_f32 v45, v70, v71
	s_waitcnt lgkmcnt(13)
	v_mfma_f32_16x16x32_bf16 v[204:207], v[30:33], v[128:131], v[204:207]
	ds_read_b64 v[30:31], v246 offset:13824
	ds_read_b64 v[32:33], v246 offset:13856
	v_pk_add_f32 v[234:235], v[234:235], v[52:53]
	v_pk_add_f32 v[234:235], v[234:235], v[54:55]
	s_waitcnt lgkmcnt(14)
	v_mfma_f32_16x16x32_bf16 v[200:203], v[34:37], v[104:107], v[200:203]
	ds_read_b64 v[34:35], v246 offset:16128
	ds_read_b64 v[36:37], v246 offset:16160
	v_pk_add_f32 v[236:237], v[236:237], v[68:69]
	v_pk_add_f32 v[236:237], v[236:237], v[70:71]
	s_waitcnt lgkmcnt(14)
	v_mfma_f32_16x16x32_bf16 v[184:187], v[6:9], v[38:41], v[184:187]
	v_exp_f32_e32 v56, v56
	v_exp_f32_e32 v57, v57
	v_mfma_f32_16x16x32_bf16 v[188:191], v[6:9], v[42:45], v[188:191]
	ds_read_b64 v[6:7], v246 offset:64
	ds_read_b64 v[8:9], v246 offset:96
	v_exp_f32_e32 v58, v58
	v_exp_f32_e32 v59, v59
	s_waitcnt lgkmcnt(14)
	v_mfma_f32_16x16x32_bf16 v[180:183], v[10:13], v[38:41], v[180:183]
	v_exp_f32_e32 v72, v72
	v_exp_f32_e32 v73, v73
	v_mfma_f32_16x16x32_bf16 v[176:179], v[10:13], v[42:45], v[176:179]
	ds_read_b64 v[10:11], v246 offset:2368
	ds_read_b64 v[12:13], v246 offset:2400
	v_exp_f32_e32 v74, v74
	v_exp_f32_e32 v75, v75
	s_waitcnt lgkmcnt(14)
; __device__ __forceinline__ void att_pv(const LAS unsigned char* Vb, int nst, const f32x4 (&sc)[2][4], f32x4 (&O)[2][8], float& l0, float& l1, int fr, int fq) {
;     constexpr int VSTR = 144;
;     if (nst <= 0) return;
;     unsigned pw[2][4][2];
; #pragma unroll
;     for (int st = 0; st < 4; ++st) {
;         if (st < nst) {
;             float p0[4], p1[4];
; #pragma unroll
;             for (int e = 0; e < 4; ++e) { p0[e] = __builtin_amdgcn_exp2f(sc[0][st][e]); p1[e] = __builtin_amdgcn_exp2f(sc[1][st][e]); l0 += p0[e]; l1 += p1[e]; }
;             pw[0][st][0] = pk2(p0[0], p0[1]); pw[0][st][1] = pk2(p0[2], p0[3]); pw[1][st][0] = pk2(p1[0], p1[1]); pw[1][st][1] = pk2(p1[2], p1[3]);
;         } else { pw[0][st][0] = 0u; pw[0][st][1] = 0u; pw[1][st][0] = 0u; pw[1][st][1] = 0u; }
;     }
; #pragma unroll
;     for (int ks2 = 0; ks2 < 2; ++ks2) {
;         if (ks2 == 0 || nst == 4) {
;             const u32x4 a0 = (u32x4){pw[0][2 * ks2][0], pw[0][2 * ks2][1], pw[0][2 * ks2 + 1][0], pw[0][2 * ks2 + 1][1]};
;             const u32x4 a1 = (u32x4){pw[1][2 * ks2][0], pw[1][2 * ks2][1], pw[1][2 * ks2 + 1][0], pw[1][2 * ks2 + 1][1]};
;             const bf16x8 pf0 = __builtin_bit_cast(bf16x8, a0), pf1 = __builtin_bit_cast(bf16x8, a1);
; #pragma unroll
;             for (int dt = 0; dt < 8; ++dt) {
;                 const LAS unsigned char* vp = Vb + (16 * dt + fr) * VSTR + (32 * ks2 + 4 * fq) * 2;
;                 const u32x2 va = *(const LAS u32x2*)vp, vb2 = *(const LAS u32x2*)(vp + 32);
;                 const bf16x8 vf = __builtin_bit_cast(bf16x8, (u32x4){va.x, va.y, vb2.x, vb2.y});
;                 O[0][dt] = __builtin_amdgcn_mfma_f32_16x16x32_bf16(vf, pf0, O[0][dt], 0, 0, 0);
;                 O[1][dt] = __builtin_amdgcn_mfma_f32_16x16x32_bf16(vf, pf1, O[1][dt], 0, 0, 0);
;             }
;         }
;     }
; }
; __device__ __forceinline__ void attn_phase(const Params& P, LAS unsigned char* lds, int tid, int wid, int lane) {
;     ...
;             if (j + 2 < nt) { if (j + 3 < nt) ATT_LOADK(a, j + 3); ATT_LOADV(a, j + 2); }
;             if (j + 2 < nt) att_qk(lds, qf, ATT_NST(j + 2), j + 2, qpos, slope2, fr, fq, scA);
;             att_pv(lds + VOFF + VBUF, ATT_NST(j + 1), scB, O, l0, l1, fr, fq);
;             if (j + 2 < nt) { if (j + 3 < nt) ATT_WRITEK(a, 1); ATT_WRITEV(a, 0); }
;             ATT_BAR();
;         }
	v_mfma_f32_16x16x32_bf16 v[164:167], v[14:17], v[38:41], v[164:167]
	v_exp_f32_e32 v60, v60
	v_exp_f32_e32 v61, v61
	v_mfma_f32_16x16x32_bf16 v[160:163], v[14:17], v[42:45], v[160:163]
	ds_read_b64 v[14:15], v246 offset:4672
	ds_read_b64 v[16:17], v246 offset:4704
	v_exp_f32_e32 v62, v62
	v_exp_f32_e32 v63, v63
	s_waitcnt lgkmcnt(14)
	v_mfma_f32_16x16x32_bf16 v[148:151], v[18:21], v[38:41], v[148:151]
	v_exp_f32_e32 v76, v76
	v_exp_f32_e32 v77, v77
	v_mfma_f32_16x16x32_bf16 v[144:147], v[18:21], v[42:45], v[144:147]
	ds_read_b64 v[18:19], v246 offset:6976
	ds_read_b64 v[20:21], v246 offset:7008
	v_exp_f32_e32 v78, v78
	v_exp_f32_e32 v79, v79
	s_waitcnt lgkmcnt(14)
	v_mfma_f32_16x16x32_bf16 v[140:143], v[22:25], v[38:41], v[140:143]
	v_cvt_pk_bf16_f32 v0, v56, v57
	v_cvt_pk_bf16_f32 v1, v58, v59
	v_mfma_f32_16x16x32_bf16 v[136:139], v[22:25], v[42:45], v[136:139]
	ds_read_b64 v[22:23], v246 offset:9280
	ds_read_b64 v[24:25], v246 offset:9312
	v_cvt_pk_bf16_f32 v230, v72, v73
	v_cvt_pk_bf16_f32 v231, v74, v75
	s_waitcnt lgkmcnt(14)
	v_mfma_f32_16x16x32_bf16 v[132:135], v[26:29], v[38:41], v[132:135]
	v_pk_add_f32 v[234:235], v[234:235], v[56:57]
	v_pk_add_f32 v[234:235], v[234:235], v[58:59]
	v_mfma_f32_16x16x32_bf16 v[124:127], v[26:29], v[42:45], v[124:127]
	ds_read_b64 v[26:27], v246 offset:11584
	ds_read_b64 v[28:29], v246 offset:11616
	v_pk_add_f32 v[236:237], v[236:237], v[72:73]
	v_pk_add_f32 v[236:237], v[236:237], v[74:75]
	s_waitcnt lgkmcnt(14)
	v_mfma_f32_16x16x32_bf16 v[120:123], v[30:33], v[38:41], v[120:123]
	v_cvt_pk_bf16_f32 v2, v60, v61
	v_cvt_pk_bf16_f32 v3, v62, v63
	v_mfma_f32_16x16x32_bf16 v[116:119], v[30:33], v[42:45], v[116:119]
	ds_read_b64 v[30:31], v246 offset:13888
	ds_read_b64 v[32:33], v246 offset:13920
	v_cvt_pk_bf16_f32 v232, v76, v77
	v_cvt_pk_bf16_f32 v233, v78, v79
	s_waitcnt lgkmcnt(14)
	v_mfma_f32_16x16x32_bf16 v[108:111], v[34:37], v[38:41], v[108:111]
	v_pk_add_f32 v[234:235], v[234:235], v[60:61]
	v_pk_add_f32 v[234:235], v[234:235], v[62:63]
	v_mfma_f32_16x16x32_bf16 v[100:103], v[34:37], v[42:45], v[100:103]
	ds_read_b64 v[34:35], v246 offset:16192
	ds_read_b64 v[36:37], v246 offset:16224
	v_pk_add_f32 v[236:237], v[236:237], v[76:77]
	v_pk_add_f32 v[236:237], v[236:237], v[78:79]
	s_add_i32 s5, s4, 2
	s_cmp_le_u32 s5, s37
	s_cselect_b32 s45, s16, s18
	s_add_i32 s0, s37, 1
	s_cmp_le_u32 s5, s0
	s_cselect_b32 s43, s16, s18
	s_waitcnt vmcnt(0)
	ds_write_b128 v251, v[84:87] offset:17408
	ds_write_b128 v251, v[88:91] offset:17536
	ds_write_b128 v252, v[92:95] offset:34816
	ds_write_b128 v252, v[96:99] offset:34880
	s_waitcnt lgkmcnt(15)
	v_mfma_f32_16x16x32_bf16 v[184:187], v[6:9], v[0:3], v[184:187]
	v_mov_b32_e32 v4, s43
	v_fma_f32 v48, |v47|, s19, v4
	v_subrev_f32_e32 v49, 0x3f800000, v47
	v_mfma_f32_16x16x32_bf16 v[188:191], v[6:9], v[230:233], v[188:191]
	v_fma_f32 v49, |v49|, s19, v4
	v_subrev_f32_e32 v50, 0x40000000, v47
	v_fma_f32 v50, |v50|, s19, v4
	s_waitcnt lgkmcnt(15)
	v_mfma_f32_16x16x32_bf16 v[180:183], v[10:13], v[0:3], v[180:183]
	v_subrev_f32_e32 v51, 0x40400000, v47
	v_fma_f32 v51, |v51|, s19, v4
	v_mfma_f32_16x16x32_bf16 v[176:179], v[10:13], v[230:233], v[176:179]
	v_mov_b32_e32 v4, s45
	v_subrev_f32_e32 v52, 0x41800000, v47
	s_waitcnt lgkmcnt(14)
	v_mfma_f32_16x16x32_bf16 v[164:167], v[14:17], v[0:3], v[164:167]
	v_fma_f32 v52, |v52|, s19, v4
	v_subrev_f32_e32 v53, 0x41880000, v47
	v_mfma_f32_16x16x32_bf16 v[160:163], v[14:17], v[230:233], v[160:163]
	v_fma_f32 v53, |v53|, s19, v4
	v_subrev_f32_e32 v54, 0x41900000, v47
	s_waitcnt lgkmcnt(12)
	v_mfma_f32_16x16x32_bf16 v[148:151], v[18:21], v[0:3], v[148:151]
	v_fma_f32 v54, |v54|, s19, v4
	v_subrev_f32_e32 v55, 0x41980000, v47
	v_mfma_f32_16x16x32_bf16 v[144:147], v[18:21], v[230:233], v[144:147]
	v_fma_f32 v55, |v55|, s19, v4
	v_subrev_f32_e32 v56, 0x42000000, v47
	s_waitcnt lgkmcnt(10)
	v_mfma_f32_16x16x32_bf16 v[140:143], v[22:25], v[0:3], v[140:143]
	v_fma_f32 v56, |v56|, s19, v4
	v_subrev_f32_e32 v57, 0x42040000, v47
	v_mfma_f32_16x16x32_bf16 v[136:139], v[22:25], v[230:233], v[136:139]
	v_fma_f32 v57, |v57|, s19, v4
	v_subrev_f32_e32 v58, 0x42080000, v47
	s_waitcnt lgkmcnt(8)
	v_mfma_f32_16x16x32_bf16 v[132:135], v[26:29], v[0:3], v[132:135]
	v_fma_f32 v58, |v58|, s19, v4
	v_subrev_f32_e32 v59, 0x420c0000, v47
	v_mfma_f32_16x16x32_bf16 v[124:127], v[26:29], v[230:233], v[124:127]
	v_fma_f32 v59, |v59|, s19, v4
	v_subrev_f32_e32 v60, 0x42400000, v47
	s_waitcnt lgkmcnt(6)
	v_mfma_f32_16x16x32_bf16 v[120:123], v[30:33], v[0:3], v[120:123]
	v_fma_f32 v60, |v60|, s19, v4
	v_subrev_f32_e32 v61, 0x42440000, v47
	v_mfma_f32_16x16x32_bf16 v[116:119], v[30:33], v[230:233], v[116:119]
	v_fma_f32 v61, |v61|, s19, v4
	v_subrev_f32_e32 v62, 0x42480000, v47
	s_waitcnt lgkmcnt(4)
	v_mfma_f32_16x16x32_bf16 v[108:111], v[34:37], v[0:3], v[108:111]
	v_fma_f32 v62, |v62|, s19, v4
	v_subrev_f32_e32 v63, 0x424c0000, v47
	v_mfma_f32_16x16x32_bf16 v[100:103], v[34:37], v[230:233], v[100:103]
	v_fma_f32 v63, |v63|, s19, v4
	v_add_f32_e32 v47, 0xc2800000, v47
	s_waitcnt lgkmcnt(0)
	s_barrier
	s_add_i32 s4, s4, 1
	s_branch .Latt_it_e
.Latt_exit:
	v_add_f32_e32 v234, v234, v235
	v_add_f32_e32 v235, v236, v237
	v_mov_b32_e32 v5, 0
	s_nop 7
	s_nop 7
	s_branch .LBB0_616
